# ph0: the 64 tail weight-conversion tiles reassigned from workgroups 0..63 (which also own the short third RMSNorm trip) to workgroups 64..127
# speedup vs baseline: 1.0074x; 1.0035x over previous
; #define LAS __attribute__((address_space(3)))
; __device__ __forceinline__ void convert_tiles(int t0, int t1, int step, LAS float* tile) {
;     int t = t0;
;     if (t < t1) {
;         TileJob cur = tile_job(t); f32x4 v[2]; tile_load(cur, v);
;         for (;;) {
;             const int tn = t + step; const bool more = tn < t1;
;             TileJob nxt = cur; f32x4 vn[2];
;             if (more) { nxt = tile_job(tn); tile_load(nxt, vn); }
;             tile_store(cur, v, tile);
;             if (!more) break;
;             cur = nxt; v[0] = vn[0]; v[1] = vn[1]; t = tn;
;         }
;     }
.LBB0_1006:
	s_add_i32 s2, s2, s82
	s_cmpk_lt_i32 s2, 0x400
	s_cbranch_scc1 .Lcvt_keep
	s_sub_i32 s2, s2, 64
	s_sub_i32 s13, s13, 0x1000
	s_cmpk_lt_i32 s2, 0x400
	s_cselect_b32 s2, 0x440, s2
.Lcvt_keep:
	s_cmpk_gt_i32 s2, 0x43f
	s_cselect_b64 s[4:5], -1, 0
	s_and_b64 vcc, exec, s[4:5]
	s_cbranch_vccnz .LBB0_1005
	s_ashr_i32 s10, s2, 31
	s_mov_b64 s[8:9], s[0:1]
	s_mov_b64 s[6:7], s[0:1]
	s_lshr_b32 s10, s10, 28
	s_add_i32 s10, s2, s10
	s_load_dwordx2 s[6:7], s[6:7], 0x48
	s_ashr_i32 s25, s10, 4
	v_mov_b32_e32 v8, v202
	s_lshl_b32 s10, s25, 6
	v_lshlrev_b32_e32 v9, 2, v8
	v_and_or_b32 v22, v9, 60, s10
	v_ashrrev_i32_e32 v8, 4, v8
	s_lshl_b32 s10, s25, 10
	v_subrev_u32_e32 v8, s10, v8
	s_movk_i32 s10, 0x100c
	v_add_u32_e32 v16, s13, v8
	v_ashrrev_i32_e32 v23, 31, v22
	v_cmp_gt_i32_e32 vcc, s10, v22
	v_mov_b32_e32 v15, 0
	v_mov_b32_e32 v8, 0
	v_mov_b32_e32 v9, 0
	v_mov_b32_e32 v10, 0
	v_mov_b32_e32 v11, 0
	s_and_saveexec_b64 s[10:11], vcc
	s_cbranch_execz .LBB0_1009
	s_waitcnt lgkmcnt(0)
	v_mov_b64_e32 v[8:9], s[6:7]
	s_movk_i32 s23, 0x4030
	v_mad_i64_i32 v[8:9], s[30:31], v16, s23, v[8:9]
	v_lshl_add_u64 v[8:9], v[22:23], 2, v[8:9]
	global_load_dwordx4 v[8:11], v[8:9], off
